# XCD-local grid barriers (census-checked, global fallback) + attention unit remap to XCD-owned batches + no setprio
# speedup vs baseline: 1.0137x; 1.0137x over previous
_Z8yoco_fwd6Params:
	s_load_dwordx16 s[76:91], s[0:1], 0x80
	s_load_dword s33, s[0:1], 0xc8
	s_load_dwordx2 s[72:73], s[0:1], 0xc0
	s_add_u32 s20, s0, 0xc0
	v_and_b32_e32 v218, 0x3ff, v0
	s_addc_u32 s21, s1, 0
	v_cmp_gt_u32_e32 vcc, 2, v218
	s_and_saveexec_b64 s[4:5], vcc
	v_lshl_add_u32 v1, v218, 2, 0
	v_add_u32_e32 v1, 0x20000, v1
	v_mov_b32_e32 v2, 0
	ds_write_b32 v1, v2
	s_or_b64 exec, exec, s[4:5]
	s_load_dwordx16 s[4:19], s[0:1], 0x0
	s_waitcnt lgkmcnt(0)
	s_barrier
	s_add_u32 s38, s90, 0x280000
	v_writelane_b32 v253, s4, 0
	s_addc_u32 s39, s91, 0
	v_cmp_eq_u32_e64 s[64:65], 0, v218
	v_writelane_b32 v253, s5, 1
	v_writelane_b32 v253, s6, 2
	v_writelane_b32 v253, s7, 3
	v_writelane_b32 v253, s8, 4
	v_writelane_b32 v253, s9, 5
	v_writelane_b32 v253, s10, 6
	v_writelane_b32 v253, s11, 7
	v_writelane_b32 v253, s12, 8
	v_writelane_b32 v253, s13, 9
	v_writelane_b32 v253, s14, 10
	v_writelane_b32 v253, s15, 11
	v_writelane_b32 v253, s16, 12
	v_writelane_b32 v253, s17, 13
	v_writelane_b32 v253, s18, 14
	v_writelane_b32 v253, s19, 15
	s_load_dwordx16 s[4:19], s[0:1], 0x40
	s_getreg_b32 s0, hwreg(HW_REG_XCC_ID, 0, 4)
	s_and_b32 s3, s0, 15
	s_mov_b32 s1, 0
	s_waitcnt lgkmcnt(0)
	v_writelane_b32 v253, s4, 16
	s_nop 1
	v_writelane_b32 v253, s5, 17
	v_writelane_b32 v253, s6, 18
	v_writelane_b32 v253, s7, 19
	v_writelane_b32 v253, s8, 20
	v_writelane_b32 v253, s9, 21
	v_writelane_b32 v253, s10, 22
	v_writelane_b32 v253, s11, 23
	v_writelane_b32 v253, s12, 24
	v_writelane_b32 v253, s13, 25
	v_writelane_b32 v253, s14, 26
	v_writelane_b32 v253, s15, 27
	v_writelane_b32 v253, s16, 28
	v_writelane_b32 v253, s17, 29
	v_writelane_b32 v253, s18, 30
	v_writelane_b32 v253, s19, 31
	s_and_saveexec_b64 s[22:23], s[64:65]
	s_cbranch_execz .LBB0_5
	s_mov_b64 s[24:25], exec
	v_mbcnt_lo_u32_b32 v1, s24, 0
	v_mbcnt_hi_u32_b32 v1, s25, v1
	v_cmp_eq_u32_e32 vcc, 0, v1
	s_and_b64 s[26:27], exec, vcc
	s_mov_b64 exec, s[26:27]
	s_cbranch_execz .LBB0_5
	s_lshl_b32 s0, s3, 8
	s_bcnt1_i32_b64 s24, s[24:25]
	v_mov_b32_e32 v1, s0
	v_mov_b32_e32 v2, s24
	global_atomic_add v1, v2, s[38:39] offset:1024
	s_and_b32 s24, s2, 7
	s_lshl_b32 s24, 1, s24
	s_lshl_b32 s0, s3, 2
	s_add_i32 s0, s0, 0x3700
	v_mov_b32_e32 v1, s0
	v_mov_b32_e32 v2, s24
	global_atomic_or v1, v2, s[38:39]

.LBB0_138:
	s_or_b64 exec, exec, s[0:1]
	s_lshl_b32 s98, s3, 2
	s_add_i32 s98, s98, 0x3700
	v_mov_b32_e32 v1, s98
	s_lshl_b32 s98, s3, 8
	s_add_i32 s98, s98, 0x400
	v_mov_b32_e32 v2, s98
	global_load_dword v1, v1, s[38:39] sc1
	global_load_dword v2, v2, s[38:39] sc1
	s_and_b32 s98, s2, 7
	s_lshl_b32 s98, 1, s98
	s_lshr_b32 s99, s72, 3
	s_waitcnt vmcnt(0)
	v_cmp_ne_u32_e32 vcc, s98, v1
	v_cmp_ne_u32_e64 s[100:101], s99, v2
	s_nop 3
	s_or_b64 vcc, vcc, s[100:101]
	s_cbranch_vccz .Lcensus_ok
	v_mov_b32_e32 v1, 0x3780
	v_mov_b32_e32 v2, 1
	global_atomic_or v1, v2, s[38:39]
.Lcensus_ok:
	s_mov_b32 s101, 0
	s_cmpk_lt_i32 s2, 0x200
	s_cselect_b64 s[4:5], -1, 0
	v_writelane_b32 v253, s4, 50
	s_lshl_b32 s1, s2, 6
	s_and_b32 s1, s1, 0x1c0
	v_writelane_b32 v253, s5, 51
	s_ashr_i32 s4, s2, 3
	s_add_i32 s1, s1, s4
	s_ashr_i32 s5, s1, 2
	s_lshl_b32 s1, s4, 1
	s_and_b32 s1, s1, 6
	v_writelane_b32 v253, s1, 52
	s_ashr_i32 s1, s5, 31
	s_add_u32 s68, s26, 0x280200
	s_addc_u32 s69, s27, 0
	s_add_u32 s70, s26, 0x280400
	s_addc_u32 s71, s27, 0
	s_add_u32 s66, s26, 0x280500
	s_addc_u32 s67, s27, 0
	s_add_u32 s34, s26, 0x280600
	s_addc_u32 s35, s27, 0
	s_add_u32 s36, s26, 0x280700
	s_addc_u32 s37, s27, 0
	s_add_u32 s56, s26, 0x280800
	s_addc_u32 s57, s27, 0
	s_add_u32 s58, s26, 0x280900
	s_addc_u32 s59, s27, 0
	s_add_u32 s60, s26, 0x280a00
	s_addc_u32 s61, s27, 0
	s_add_u32 s76, s26, 0x280b00
	s_addc_u32 s77, s27, 0
	s_add_u32 s78, s26, 0x280c00
	s_addc_u32 s79, s27, 0
	s_add_u32 s80, s26, 0x280d00
	s_addc_u32 s81, s27, 0
	s_add_u32 s82, s26, 0x280e00
	s_addc_u32 s83, s27, 0
	s_add_u32 s84, s26, 0x280f00
	s_addc_u32 s85, s27, 0
	s_add_u32 s86, s26, 0x281000
	s_addc_u32 s87, s27, 0
	s_add_u32 s88, s26, 0x281100
	s_addc_u32 s89, s27, 0
	s_add_u32 s90, s26, 0x281200
	s_addc_u32 s91, s27, 0
	s_add_u32 s92, s26, 0x281300
	s_addc_u32 s93, s27, 0
	s_mul_i32 s0, s73, s72
	v_writelane_b32 v253, s5, 54
	s_cmp_eq_u32 s3, 15
	v_writelane_b32 v253, s1, 56
	s_mul_i32 s94, s0, s33
	s_cselect_b64 s[0:1], -1, 0
	v_writelane_b32 v253, s0, 58
	s_cmp_eq_u32 s3, 14
	s_movk_i32 s53, 0x161
	v_writelane_b32 v253, s1, 59
	s_cselect_b64 s[0:1], -1, 0
	v_writelane_b32 v253, s0, 60
	s_cmp_eq_u32 s3, 13
	v_mov_b32_e32 v177, 0
	v_writelane_b32 v253, s1, 61
	s_cselect_b64 s[0:1], -1, 0
	v_writelane_b32 v253, s0, 62
	s_cmp_eq_u32 s3, 12
	v_mov_b32_e32 v220, 0x358637bd
	v_writelane_b32 v253, s1, 63
	s_cselect_b64 s[0:1], -1, 0
	v_writelane_b32 v254, s0, 0
	s_cmp_eq_u32 s3, 11
	v_writelane_b32 v253, s60, 16
	v_writelane_b32 v254, s1, 1
	s_cselect_b64 s[0:1], -1, 0
	v_writelane_b32 v254, s0, 2
	s_cmp_eq_u32 s3, 10
	v_mov_b32_e32 v221, 1
	v_writelane_b32 v254, s1, 3
	s_cselect_b64 s[0:1], -1, 0
	v_writelane_b32 v254, s0, 4
	s_cmp_eq_u32 s3, 9
	v_mbcnt_hi_u32_b32 v219, -1, v51
	v_writelane_b32 v254, s1, 5
	s_cselect_b64 s[0:1], -1, 0
	v_writelane_b32 v254, s0, 6
	s_cmp_eq_u32 s3, 8
	v_mov_b64_e32 v[178:179], 0x1ff
	v_writelane_b32 v254, s1, 7
	s_cselect_b64 s[0:1], -1, 0
	v_writelane_b32 v254, s0, 8
	s_cmp_eq_u32 s3, 7
	v_mov_b64_e32 v[180:181], 0x200
	v_writelane_b32 v254, s1, 9
	s_cselect_b64 s[0:1], -1, 0
	v_writelane_b32 v254, s0, 10
	s_cmp_eq_u32 s3, 6
	v_mov_b64_e32 v[182:183], 0xb00
	v_writelane_b32 v254, s1, 11
	s_cselect_b64 s[0:1], -1, 0
	v_writelane_b32 v254, s0, 12
	s_cmp_eq_u32 s3, 5
	v_mov_b64_e32 v[184:185], 0xaff
	v_writelane_b32 v254, s1, 13
	s_cselect_b64 s[0:1], -1, 0
	v_writelane_b32 v254, s0, 14
	s_cmp_eq_u32 s3, 4
	s_mov_b32 s17, 0
	v_writelane_b32 v254, s1, 15
	s_cselect_b64 s[0:1], -1, 0
	v_writelane_b32 v254, s0, 16
	s_cmp_eq_u32 s3, 3
	s_mov_b64 s[14:15], 0x80
	v_writelane_b32 v254, s1, 17
	s_cselect_b64 s[0:1], -1, 0
	v_writelane_b32 v254, s0, 18
	s_cmp_eq_u32 s3, 2
	v_writelane_b32 v253, s61, 17
	v_writelane_b32 v254, s1, 19
	s_cselect_b64 s[0:1], -1, 0
	v_writelane_b32 v254, s0, 20
	s_cmp_eq_u32 s3, 1
	s_barrier
	v_writelane_b32 v254, s1, 21
	s_cselect_b64 s[0:1], -1, 0
	v_writelane_b32 v254, s0, 22
	s_cmp_eq_u32 s3, 0
	s_nop 0
	v_writelane_b32 v254, s1, 23
	s_cselect_b64 s[0:1], -1, 0
	v_writelane_b32 v254, s0, 24
	s_nop 1
	v_writelane_b32 v254, s1, 25
	s_lshl_b32 s0, s3, 8
	s_add_u32 s0, s38, s0
	s_addc_u32 s1, s39, 0
	s_add_u32 s4, s0, 0x1400
	s_addc_u32 s5, s1, 0
	v_writelane_b32 v254, s4, 26
	s_add_u32 s0, s0, 0x2400
	s_addc_u32 s1, s1, 0
	v_writelane_b32 v254, s5, 27
	v_writelane_b32 v254, s0, 28
	s_nop 1
	v_writelane_b32 v254, s1, 29
	s_add_u32 s0, s26, 0x283400
	s_addc_u32 s1, s27, 0
	v_writelane_b32 v254, s0, 30
	s_nop 1
	v_writelane_b32 v254, s1, 31
	s_add_u32 s0, s26, 0x283500
	s_addc_u32 s1, s27, 0
	v_writelane_b32 v254, s0, 32
	s_ashr_i32 s3, s2, 31
	s_ashr_i32 s73, s72, 31
	v_writelane_b32 v254, s1, 33
	s_lshr_b32 s0, s3, 29
	s_add_i32 s0, s2, s0
	s_ashr_i32 s7, s0, 3
	s_and_b32 s0, s0, -8
	s_sub_i32 s8, s2, s0
	s_cmp_gt_i32 s8, -1
	s_cselect_b64 s[0:1], -1, 0
	s_lshl_b32 s4, s8, 6
	v_writelane_b32 v254, s0, 34
	s_cmpk_lt_i32 s2, 0xb00
	s_nop 0
	v_writelane_b32 v254, s1, 35
	s_cselect_b64 s[0:1], -1, 0
	v_writelane_b32 v254, s0, 36
	s_cmp_lt_i32 s8, 0
	s_nop 0
	v_writelane_b32 v254, s1, 37
	s_cselect_b64 s[0:1], -1, 0
	v_writelane_b32 v254, s0, 38
	s_nop 1
	v_writelane_b32 v254, s1, 39
	s_and_b64 s[0:1], s[0:1], exec
	s_mul_i32 s0, s8, 0x41
	s_cselect_b32 s0, s0, s4
	s_cselect_b32 s1, s53, 0x160
	s_add_i32 s5, s0, s7
	s_ashr_i32 s0, s5, 31
	v_writelane_b32 v254, s0, 40
	s_lshr_b32 s0, s0, 27
	s_add_i32 s0, s5, s0
	s_and_b32 s4, s0, 0xffe0
	s_sub_i32 s4, s5, s4
	v_writelane_b32 v254, s5, 42
	s_bfe_i32 s5, s4, 0x80000
	s_bfe_u32 s5, s5, 0x3000c
	s_add_i32 s5, s4, s5
	s_and_b32 s6, s5, 0xf8
	s_sub_i32 s4, s4, s6
	s_ashr_i32 s0, s0, 5
	s_lshl_b32 s0, s0, 3
	s_sext_i32_i8 s4, s4
	s_add_i32 s95, s0, s4
	s_mul_i32 s0, s8, s1
	s_add_i32 s0, s0, s7
	s_mul_hi_i32 s1, s0, 0x2e8ba2e9
	s_lshr_b32 s4, s1, 31
	s_ashr_i32 s1, s1, 5
	s_add_i32 s1, s1, s4
	s_mul_i32 s4, s1, 0xb0
	s_sub_i32 s0, s0, s4
	s_bfe_u32 s4, s0, 0x3001c
	s_add_i32 s4, s0, s4
	s_and_b32 s6, s4, 0xfff8
	s_sub_i32 s0, s0, s6
	s_lshl_b32 s1, s1, 3
	s_sext_i32_i16 s0, s0
	v_writelane_b32 v254, s8, 44
	s_add_i32 s8, s1, s0
	s_bfe_i32 s0, s5, 0x80000
	s_sext_i32_i16 s1, s0
	s_sext_i32_i16 s0, s4
	v_writelane_b32 v254, s7, 45
	s_ashr_i32 s4, s0, 3
	s_lshr_b32 s0, s0, 3
	v_writelane_b32 v254, s4, 46
	s_bfe_i64 s[4:5], s[0:1], 0x100000
	v_writelane_b32 v254, s4, 47
	s_ashr_i32 s0, s1, 3
	s_mov_b64 s[6:7], -1
	v_writelane_b32 v254, s5, 48
	v_writelane_b32 v254, s0, 49
	s_lshr_b32 s0, s1, 3
	s_bfe_i64 s[0:1], s[0:1], 0x100000
	v_writelane_b32 v254, s0, 50
	s_nop 1
	v_writelane_b32 v254, s1, 51
	s_ashr_i32 s0, s8, 31
	v_writelane_b32 v254, s0, 52
	s_ashr_i32 s0, s95, 31
	v_writelane_b32 v254, s0, 53
	s_add_i32 s0, 0, 0x20000
	v_writelane_b32 v254, s0, 54
	s_add_i32 s0, 0, 0x20004
	v_writelane_b32 v254, s0, 55
	v_writelane_b32 v254, s94, 56
	v_writelane_b32 v254, s68, 57
	s_mov_b32 s0, 0
	s_nop 0
	v_writelane_b32 v254, s69, 58
	v_writelane_b32 v254, s70, 59
	s_nop 1
	v_writelane_b32 v254, s71, 60
	v_writelane_b32 v254, s66, 61
	s_nop 1
	v_writelane_b32 v254, s67, 62
	v_writelane_b32 v254, s34, 63
	s_nop 1
	v_writelane_b32 v255, s35, 0
	v_writelane_b32 v255, s56, 1
	s_nop 1
	v_writelane_b32 v255, s57, 2
	v_writelane_b32 v255, s58, 3
	s_nop 1
	v_writelane_b32 v255, s59, 4
	v_writelane_b32 v255, s95, 5
	v_writelane_b32 v255, s8, 6
	v_writelane_b32 v255, s36, 7
	s_nop 1
	v_writelane_b32 v255, s37, 8
	s_branch .LBB0_141

.LBB0_210:
	s_andn2_saveexec_b64 s[4:5], s[8:9]
	s_cbranch_execz .LBB0_230
	s_mov_b64 s[8:9], exec
	s_cmp_lg_u32 s101, 0
	s_cbranch_scc1 .Lxl_0
	buffer_wbl2 sc1
	s_waitcnt lgkmcnt(0)
	s_waitcnt vmcnt(0)
	v_mbcnt_lo_u32_b32 v1, s8, 0
	v_mbcnt_hi_u32_b32 v1, s9, v1
	v_cmp_eq_u32_e32 vcc, 0, v1
	s_and_saveexec_b64 s[10:11], vcc
	s_cbranch_execz .LBB0_213
	s_bcnt1_i32_b64 s4, s[8:9]
	v_mov_b32_e32 v2, s4
	v_readlane_b32 s4, v254, 30
	v_readlane_b32 s5, v254, 31
	s_nop 4
	global_atomic_add v2, v177, v2, s[4:5] sc0

.Lxl_0:
	s_mov_b64 s[8:9], exec
	v_mbcnt_lo_u32_b32 v0, s8, 0
	v_mbcnt_hi_u32_b32 v0, s9, v0
	v_cmp_eq_u32_e32 vcc, 0, v0
	s_waitcnt vmcnt(0)
	buffer_inv sc1
	s_and_saveexec_b64 s[10:11], vcc
	s_cbranch_execz .LBB0_229
	s_bcnt1_i32_b64 s4, s[8:9]
	v_mov_b32_e32 v0, s4
	v_readlane_b32 s4, v254, 28
	v_readlane_b32 s5, v254, 29
	s_nop 4
	global_atomic_add v177, v0, s[4:5]

.LBB0_230:
	s_or_b64 exec, exec, s[0:1]
	v_readlane_b32 s56, v253, 32
	s_xor_b64 s[0:1], s[6:7], -1
	v_readlane_b32 s70, v253, 46
	v_readlane_b32 s71, v253, 47
	v_writelane_b32 v255, s0, 18
	s_mov_b64 s[6:7], s[70:71]
	s_waitcnt lgkmcnt(0)
	v_writelane_b32 v255, s1, 19
	s_barrier
	s_add_u32 s98, s6, 0x283780
	s_addc_u32 s99, s7, 0
	v_mov_b32_e32 v1, 0
	global_load_dword v1, v1, s[98:99] sc1
	s_waitcnt vmcnt(0)
	v_readfirstlane_b32 s98, v1
	s_nop 3
	s_cmp_eq_u32 s98, 0
	s_cselect_b32 s101, 1, 0
	s_add_u32 s8, s6, 0x12d00000
	v_mov_b32_e32 v24, v218
	s_movk_i32 s0, 0x100
	s_addc_u32 s9, s7, 0
	v_readlane_b32 s57, v253, 33
	v_cmp_gt_i32_e32 vcc, s0, v24
	v_readlane_b32 s58, v253, 34
	v_readlane_b32 s59, v253, 35
	v_readlane_b32 s60, v253, 36
	v_readlane_b32 s61, v253, 37
	v_readlane_b32 s62, v253, 38
	v_readlane_b32 s63, v253, 39
	v_readlane_b32 s64, v253, 40
	v_readlane_b32 s65, v253, 41
	v_readlane_b32 s66, v253, 42
	v_readlane_b32 s67, v253, 43
	v_readlane_b32 s68, v253, 44
	v_readlane_b32 s69, v253, 45
	s_and_saveexec_b64 s[0:1], vcc
	s_xor_b64 s[0:1], exec, s[0:1]
	s_cbranch_execz .LBB0_243
	v_lshlrev_b32_e32 v0, 3, v24
	v_and_b32_e32 v32, 0x3f8, v0
	v_lshlrev_b32_e32 v20, 2, v32
	global_load_dwordx4 v[0:3], v20, s[22:23] offset:16
	global_load_dwordx4 v[4:7], v20, s[22:23]
	global_load_dwordx4 v[8:11], v20, s[20:21] offset:16
	global_load_dwordx4 v[12:15], v20, s[20:21]
	global_load_dwordx4 v[16:19], v20, s[18:19] offset:16
	s_nop 0
	global_load_dwordx4 v[20:23], v20, s[18:19]
	s_add_u32 s12, s6, 0xa900000
	s_addc_u32 s13, s7, 0
	s_add_u32 s18, s6, 0xe900000
	s_addc_u32 s19, s7, 0
	v_ashrrev_i32_e32 v33, 7, v24
	s_mov_b64 s[20:21], s[2:3]
	s_branch .LBB0_234

.LBB0_360:
	s_andn2_saveexec_b64 s[4:5], s[6:7]
	s_cbranch_execz .LBB0_380
	s_mov_b64 s[6:7], exec
	s_cmp_lg_u32 s101, 0
	s_cbranch_scc1 .Lxl_1
	buffer_wbl2 sc1
	s_waitcnt lgkmcnt(0)
	s_waitcnt vmcnt(0)
	v_mbcnt_lo_u32_b32 v1, s6, 0
	v_mbcnt_hi_u32_b32 v1, s7, v1
	v_cmp_eq_u32_e32 vcc, 0, v1
	s_and_saveexec_b64 s[8:9], vcc
	s_cbranch_execz .LBB0_363
	s_bcnt1_i32_b64 s4, s[6:7]
	v_mov_b32_e32 v2, s4
	v_readlane_b32 s4, v254, 30
	v_readlane_b32 s5, v254, 31
	s_nop 4
	global_atomic_add v2, v177, v2, s[4:5] sc0

.Lxl_1:
	s_mov_b64 s[6:7], exec
	v_mbcnt_lo_u32_b32 v0, s6, 0
	v_mbcnt_hi_u32_b32 v0, s7, v0
	v_cmp_eq_u32_e32 vcc, 0, v0
	s_waitcnt vmcnt(0)
	buffer_inv sc1
	s_and_saveexec_b64 s[8:9], vcc
	s_cbranch_execz .LBB0_379
	s_bcnt1_i32_b64 s4, s[6:7]
	v_mov_b32_e32 v0, s4
	v_readlane_b32 s4, v254, 28
	v_readlane_b32 s5, v254, 29
	s_nop 4
	global_atomic_add v177, v0, s[4:5]

.Lxl_3:
	s_mov_b64 s[6:7], exec
	v_mbcnt_lo_u32_b32 v0, s6, 0
	v_mbcnt_hi_u32_b32 v0, s7, v0
	v_cmp_eq_u32_e32 vcc, 0, v0
	s_waitcnt vmcnt(0)
	buffer_inv sc1
	s_and_saveexec_b64 s[8:9], vcc
	s_cbranch_execz .LBB0_139
	s_bcnt1_i32_b64 s4, s[6:7]
	v_mov_b32_e32 v0, s4
	v_readlane_b32 s4, v254, 28
	v_readlane_b32 s5, v254, 29
	s_nop 4
	global_atomic_add v177, v0, s[4:5]
	s_branch .LBB0_139

.LBB0_759:
	s_andn2_saveexec_b64 s[6:7], s[6:7]
	s_cbranch_execz .LBB0_779
	s_mov_b64 s[6:7], exec
	s_cmp_lg_u32 s101, 0
	s_cbranch_scc1 .Lxl_4
	buffer_wbl2 sc1
	s_waitcnt lgkmcnt(0)
	s_waitcnt vmcnt(0)
	v_mbcnt_lo_u32_b32 v1, s6, 0
	v_mbcnt_hi_u32_b32 v1, s7, v1
	v_cmp_eq_u32_e32 vcc, 0, v1
	s_and_saveexec_b64 s[8:9], vcc
	s_cbranch_execz .LBB0_762
	s_bcnt1_i32_b64 s4, s[6:7]
	v_readlane_b32 s6, v254, 30
	v_mov_b32_e32 v2, s4
	v_readlane_b32 s7, v254, 31
	s_nop 4
	global_atomic_add v2, v181, v2, s[6:7] sc0

.Lxl_4:
	s_mov_b64 s[6:7], exec
	v_mbcnt_lo_u32_b32 v0, s6, 0
	v_mbcnt_hi_u32_b32 v0, s7, v0
	v_cmp_eq_u32_e32 vcc, 0, v0
	s_waitcnt vmcnt(0)
	buffer_inv sc1
	s_and_saveexec_b64 s[8:9], vcc
	s_cbranch_execz .LBB0_778
	s_bcnt1_i32_b64 s4, s[6:7]
	v_readlane_b32 s6, v254, 28
	v_mov_b32_e32 v0, s4
	v_readlane_b32 s7, v254, 29
	s_nop 4
	global_atomic_add v181, v0, s[6:7]

.LBB0_935:
	s_or_b64 exec, exec, s[0:1]
	v_readlane_b32 s16, v253, 32
	v_readlane_b32 s0, v254, 42
	v_readlane_b32 s30, v253, 46
	v_readlane_b32 s31, v253, 47
	v_readlane_b32 s1, v254, 43
	s_mov_b64 s[6:7], s[30:31]
	s_andn2_b64 vcc, exec, s[0:1]
	s_waitcnt lgkmcnt(0)
	s_barrier
	v_readlane_b32 s17, v253, 33
	v_readlane_b32 s18, v253, 34
	v_readlane_b32 s19, v253, 35
	v_readlane_b32 s20, v253, 36
	v_readlane_b32 s21, v253, 37
	v_readlane_b32 s22, v253, 38
	v_readlane_b32 s23, v253, 39
	v_readlane_b32 s24, v253, 40
	v_readlane_b32 s25, v253, 41
	v_readlane_b32 s26, v253, 42
	v_readlane_b32 s27, v253, 43
	v_readlane_b32 s28, v253, 44
	v_readlane_b32 s29, v253, 45
	s_cbranch_vccnz .LBB0_983
	s_add_u32 s8, s6, 0x12d00000
	s_addc_u32 s9, s7, 0
	s_add_u32 s4, s6, 0xa900000
	s_addc_u32 s33, s7, 0
	s_add_u32 s44, s6, 0x12900000
	s_addc_u32 s45, s7, 0
	s_add_u32 s46, s6, 0xe900000
	s_addc_u32 s47, s7, 0
	s_add_u32 s14, s6, 0x18d00000
	s_addc_u32 s15, s7, 0
	v_readlane_b32 s48, v255, 10
	s_and_b32 s100, s2, 7
	s_lshl_b32 s100, s100, 5
	s_add_i32 s48, s48, s100
	s_add_i32 s100, s48, 64
	s_branch .LBB0_938
.LBB0_937:
	ds_bpermute_b32 v64, v205, v206
	s_mov_b32 s1, s65
	v_lshlrev_b32_e32 v180, 1, v194
	s_add_i32 s48, s48, 32
	s_cmp_lt_i32 s48, s100
	s_waitcnt lgkmcnt(0)
	v_add_f32_e32 v64, v206, v64
	v_div_scale_f32 v65, s[10:11], v64, v64, 1.0
	v_rcp_f32_e32 v66, v65
	s_nop 0
	v_fma_f32 v67, -v65, v66, 1.0
	v_fmac_f32_e32 v66, v67, v66
	v_div_scale_f32 v67, vcc, 1.0, v64, 1.0
	v_mul_f32_e32 v68, v67, v66
	v_fma_f32 v69, -v65, v68, v67
	v_fmac_f32_e32 v68, v69, v66
	v_fma_f32 v65, -v65, v68, v67
	v_div_fmas_f32 v65, v65, v66, v68
	v_div_fixup_f32 v64, v65, v64, 1.0
	v_lshlrev_b64 v[66:67], 11, v[196:197]
	v_pk_mul_f32 v[48:49], v[48:49], v[64:65] op_sel_hi:[1,0]
	v_pk_mul_f32 v[50:51], v[50:51], v[64:65] op_sel_hi:[1,0]
	v_pk_mul_f32 v[32:33], v[32:33], v[64:65] op_sel_hi:[1,0]
	v_pk_mul_f32 v[34:35], v[34:35], v[64:65] op_sel_hi:[1,0]
	v_pk_mul_f32 v[16:17], v[16:17], v[64:65] op_sel_hi:[1,0]
	v_pk_mul_f32 v[18:19], v[18:19], v[64:65] op_sel_hi:[1,0]
	v_pk_mul_f32 v[0:1], v[0:1], v[64:65] op_sel_hi:[1,0]
	v_pk_mul_f32 v[2:3], v[2:3], v[64:65] op_sel_hi:[1,0]
	v_lshl_add_u64 v[66:67], s[14:15], 0, v[66:67]
	v_cvt_pk_bf16_f32 v48, v48, v49
	v_cvt_pk_bf16_f32 v49, v50, v51
	v_pk_mul_f32 v[50:51], v[52:53], v[64:65] op_sel_hi:[1,0]
	v_pk_mul_f32 v[52:53], v[54:55], v[64:65] op_sel_hi:[1,0]
	v_cvt_pk_bf16_f32 v32, v32, v33
	v_cvt_pk_bf16_f32 v33, v34, v35
	v_pk_mul_f32 v[34:35], v[36:37], v[64:65] op_sel_hi:[1,0]
	v_pk_mul_f32 v[36:37], v[38:39], v[64:65] op_sel_hi:[1,0]
	v_cvt_pk_bf16_f32 v16, v16, v17
	v_cvt_pk_bf16_f32 v17, v18, v19
	v_pk_mul_f32 v[18:19], v[20:21], v[64:65] op_sel_hi:[1,0]
	v_pk_mul_f32 v[20:21], v[22:23], v[64:65] op_sel_hi:[1,0]
	v_cvt_pk_bf16_f32 v0, v0, v1
	v_cvt_pk_bf16_f32 v1, v2, v3
	v_pk_mul_f32 v[2:3], v[4:5], v[64:65] op_sel_hi:[1,0]
	v_pk_mul_f32 v[4:5], v[6:7], v[64:65] op_sel_hi:[1,0]
	v_lshl_add_u64 v[66:67], v[66:67], 0, s[0:1]
	v_cvt_pk_bf16_f32 v50, v50, v51
	v_cvt_pk_bf16_f32 v51, v52, v53
	v_cvt_pk_bf16_f32 v34, v34, v35
	v_cvt_pk_bf16_f32 v35, v36, v37
	v_cvt_pk_bf16_f32 v18, v18, v19
	v_cvt_pk_bf16_f32 v19, v20, v21
	v_cvt_pk_bf16_f32 v2, v2, v3
	v_cvt_pk_bf16_f32 v3, v4, v5
	v_lshl_add_u64 v[66:67], v[66:67], 0, v[180:181]
	v_permlane32_swap_b32_e32 v48, v50
	v_permlane32_swap_b32_e32 v49, v51
	v_permlane32_swap_b32_e32 v32, v34
	v_permlane32_swap_b32_e32 v33, v35
	v_permlane32_swap_b32_e32 v16, v18
	v_permlane32_swap_b32_e32 v17, v19
	v_permlane32_swap_b32_e32 v0, v2
	v_permlane32_swap_b32_e32 v1, v3
	global_store_dwordx4 v[66:67], v[48:51], off
	global_store_dwordx4 v[66:67], v[32:35], off offset:64
	global_store_dwordx4 v[66:67], v[16:19], off offset:128
	v_pk_mul_f32 v[48:49], v[56:57], v[64:65] op_sel_hi:[1,0]
	v_pk_mul_f32 v[50:51], v[58:59], v[64:65] op_sel_hi:[1,0]
	v_pk_mul_f32 v[32:33], v[40:41], v[64:65] op_sel_hi:[1,0]
	v_pk_mul_f32 v[34:35], v[42:43], v[64:65] op_sel_hi:[1,0]
	v_pk_mul_f32 v[16:17], v[24:25], v[64:65] op_sel_hi:[1,0]
	v_pk_mul_f32 v[18:19], v[26:27], v[64:65] op_sel_hi:[1,0]
	global_store_dwordx4 v[66:67], v[0:3], off offset:192
	v_cvt_pk_bf16_f32 v48, v48, v49
	v_cvt_pk_bf16_f32 v49, v50, v51
	v_pk_mul_f32 v[0:1], v[8:9], v[64:65] op_sel_hi:[1,0]
	v_pk_mul_f32 v[2:3], v[10:11], v[64:65] op_sel_hi:[1,0]
	v_pk_mul_f32 v[50:51], v[60:61], v[64:65] op_sel_hi:[1,0]
	v_pk_mul_f32 v[52:53], v[62:63], v[64:65] op_sel_hi:[1,0]
	v_cvt_pk_bf16_f32 v32, v32, v33
	v_cvt_pk_bf16_f32 v33, v34, v35
	v_pk_mul_f32 v[34:35], v[44:45], v[64:65] op_sel_hi:[1,0]
	v_pk_mul_f32 v[36:37], v[46:47], v[64:65] op_sel_hi:[1,0]
	v_cvt_pk_bf16_f32 v16, v16, v17
	v_cvt_pk_bf16_f32 v17, v18, v19
	v_pk_mul_f32 v[18:19], v[28:29], v[64:65] op_sel_hi:[1,0]
	v_pk_mul_f32 v[20:21], v[30:31], v[64:65] op_sel_hi:[1,0]
	v_cvt_pk_bf16_f32 v0, v0, v1
	v_cvt_pk_bf16_f32 v1, v2, v3
	v_pk_mul_f32 v[2:3], v[12:13], v[64:65] op_sel_hi:[1,0]
	v_pk_mul_f32 v[4:5], v[14:15], v[64:65] op_sel_hi:[1,0]
	v_cvt_pk_bf16_f32 v50, v50, v51
	v_cvt_pk_bf16_f32 v51, v52, v53
	v_cvt_pk_bf16_f32 v34, v34, v35
	v_cvt_pk_bf16_f32 v35, v36, v37
	v_cvt_pk_bf16_f32 v18, v18, v19
	v_cvt_pk_bf16_f32 v19, v20, v21
	v_cvt_pk_bf16_f32 v2, v2, v3
	v_cvt_pk_bf16_f32 v3, v4, v5
	v_permlane32_swap_b32_e32 v48, v50
	v_permlane32_swap_b32_e32 v49, v51
	v_permlane32_swap_b32_e32 v32, v34
	v_permlane32_swap_b32_e32 v33, v35
	v_permlane32_swap_b32_e32 v16, v18
	v_permlane32_swap_b32_e32 v17, v19
	v_permlane32_swap_b32_e32 v0, v2
	v_permlane32_swap_b32_e32 v1, v3
	global_store_dwordx4 v[66:67], v[48:51], off offset:32
	global_store_dwordx4 v[66:67], v[32:35], off offset:96
	global_store_dwordx4 v[66:67], v[16:19], off offset:160
	global_store_dwordx4 v[66:67], v[0:3], off offset:224
	s_cbranch_scc0 .LBB0_982

	.amdhsa_kernel _Z8yoco_fwd6Params
		.amdhsa_group_segment_fixed_size 0
		.amdhsa_private_segment_fixed_size 0
		.amdhsa_kernarg_size 448
		.amdhsa_user_sgpr_count 2
		.amdhsa_user_sgpr_dispatch_ptr 0
		.amdhsa_user_sgpr_queue_ptr 0
		.amdhsa_user_sgpr_kernarg_segment_ptr 1
		.amdhsa_user_sgpr_dispatch_id 0
		.amdhsa_user_sgpr_kernarg_preload_length 0
		.amdhsa_user_sgpr_kernarg_preload_offset 0
		.amdhsa_user_sgpr_private_segment_size 0
		.amdhsa_uses_dynamic_stack 0
		.amdhsa_enable_private_segment 0
		.amdhsa_system_sgpr_workgroup_id_x 1
		.amdhsa_system_sgpr_workgroup_id_y 0
		.amdhsa_system_sgpr_workgroup_id_z 0
		.amdhsa_system_sgpr_workgroup_info 0
		.amdhsa_system_vgpr_workitem_id 2
		.amdhsa_next_free_vgpr 256
		.amdhsa_next_free_sgpr 102
		.amdhsa_accum_offset 256
		.amdhsa_reserve_vcc 1
		.amdhsa_float_round_mode_32 0
		.amdhsa_float_round_mode_16_64 0
		.amdhsa_float_denorm_mode_32 3
		.amdhsa_float_denorm_mode_16_64 3
		.amdhsa_dx10_clamp 1
		.amdhsa_ieee_mode 1
		.amdhsa_fp16_overflow 0
		.amdhsa_tg_split 0
		.amdhsa_exception_fp_ieee_invalid_op 0
		.amdhsa_exception_fp_denorm_src 0
		.amdhsa_exception_fp_ieee_div_zero 0
		.amdhsa_exception_fp_ieee_overflow 0
		.amdhsa_exception_fp_ieee_underflow 0
		.amdhsa_exception_fp_ieee_inexact 0
		.amdhsa_exception_int_div_zero 0
	.end_amdhsa_kernel

amdhsa.kernels:
  - .agpr_count:     0
    .args:
      - .offset:         0
        .size:           192
        .value_kind:     by_value
      - .offset:         192
        .size:           4
        .value_kind:     hidden_block_count_x
      - .offset:         196
        .size:           4
        .value_kind:     hidden_block_count_y
      - .offset:         200
        .size:           4
        .value_kind:     hidden_block_count_z
      - .offset:         204
        .size:           2
        .value_kind:     hidden_group_size_x
      - .offset:         206
        .size:           2
        .value_kind:     hidden_group_size_y
      - .offset:         208
        .size:           2
        .value_kind:     hidden_group_size_z
      - .offset:         210
        .size:           2
        .value_kind:     hidden_remainder_x
      - .offset:         212
        .size:           2
        .value_kind:     hidden_remainder_y
      - .offset:         214
        .size:           2
        .value_kind:     hidden_remainder_z
      - .offset:         232
        .size:           8
        .value_kind:     hidden_global_offset_x
      - .offset:         240
        .size:           8
        .value_kind:     hidden_global_offset_y
      - .offset:         248
        .size:           8
        .value_kind:     hidden_global_offset_z
      - .offset:         256
        .size:           2
        .value_kind:     hidden_grid_dims
      - .offset:         280
        .size:           8
        .value_kind:     hidden_multigrid_sync_arg
      - .offset:         312
        .size:           4
        .value_kind:     hidden_dynamic_lds_size
    .group_segment_fixed_size: 0
    .kernarg_segment_align: 8
    .kernarg_segment_size: 448
    .language:       OpenCL C
    .language_version:
      - 2
      - 0
    .max_flat_workgroup_size: 512
    .name:           _Z8yoco_fwd6Params
    .private_segment_fixed_size: 0
    .sgpr_count:     108
    .sgpr_spill_count: 165
    .symbol:         _Z8yoco_fwd6Params.kd
    .uniform_work_group_size: 1
    .uses_dynamic_stack: false
    .vgpr_count:     256
    .vgpr_spill_count: 0
    .wavefront_size: 64
